# also issue K-tile 1 prologue DMAs together with K-tile 0 in the three GEMM phases (one cold round trip instead of two)
# baseline (speedup 1.0000x reference)
.LBB0_243:
	v_readlane_b32 s0, v255, 11
	v_readlane_b32 s3, v255, 14
	s_lshl_b32 s0, s0, 1
	s_ashr_i32 s7, s3, 1
	s_add_i32 s7, s7, s0
	v_readlane_b32 s0, v252, 60
	v_readlane_b32 s1, v252, 61
	s_andn2_b64 vcc, exec, s[0:1]
	v_readfirstlane_b32 s2, v210
	s_cbranch_vccnz .LBB0_269
	v_lshlrev_b32_e32 v2, 4, v210
	s_waitcnt vmcnt(15)
	v_add_u32_e32 v20, 0x2000, v2
	v_ashrrev_i32_e32 v21, 31, v20
	v_lshrrev_b32_e32 v21, 22, v21
	v_add_u32_e32 v21, v20, v21
	s_waitcnt vmcnt(10)
	v_ashrrev_i32_e32 v24, 10, v21
	v_mul_i32_i24_e32 v21, 0x400, v24
	v_sub_u32_e32 v20, v20, v21
	v_lshrrev_b32_e32 v21, 4, v20
	v_bitop3_b32 v20, v21, v20, 32 bitop3:0x6c
	v_ashrrev_i32_e32 v21, 31, v20
	v_lshrrev_b32_e32 v21, 26, v21
	s_ashr_i32 s3, s2, 6
	v_add_u32_e32 v21, v20, v21
	v_lshlrev_b32_e32 v22, 3, v24
	s_lshl_b32 s28, s3, 10
	s_mul_i32 s1, s7, 0x4200000
	v_readlane_b32 s6, v252, 58
	v_ashrrev_i32_e32 v25, 6, v21
	v_and_b32_e32 v22, -16, v22
	s_mul_hi_i32 s0, s7, 0x4200000
	s_add_u32 s29, s6, s1
	v_readlane_b32 s1, v252, 59
	v_add_u32_e32 v22, v25, v22
	s_addc_u32 s38, s1, s0
	v_and_b32_e32 v23, 3, v25
	s_mov_b32 s0, 0xfffe0
	s_waitcnt vmcnt(9)
	v_lshrrev_b32_e32 v26, 2, v22
	v_lshlrev_b32_e32 v27, 1, v22
	v_and_b32_e32 v21, 0xc0, v21
	v_and_or_b32 v23, v22, s0, v23
	v_and_b32_e32 v26, 4, v26
	v_and_b32_e32 v27, 24, v27
	v_sub_u32_e32 v20, v20, v21
	s_waitcnt vmcnt(8)
	v_mov_b32_e32 v30, 1
	v_or3_b32 v23, v23, v26, v27
	v_lshlrev_b32_e32 v26, 5, v24
	v_ashrrev_i16_sdwa v20, v30, sext(v20) dst_sel:DWORD dst_unused:UNUSED_PAD src0_sel:DWORD src1_sel:BYTE_0
	v_and_b32_e32 v27, 32, v26
	v_bfe_i32 v26, v20, 0, 16
	v_add_lshl_u32 v20, v27, v26, 1
	v_lshl_add_u32 v156, v23, 12, v20
	v_lshl_add_u32 v158, v22, 12, v20
	v_bfe_i32 v20, v210, 27, 1
	v_lshrrev_b32_e32 v20, 22, v20
	v_add_u32_e32 v20, v2, v20
	v_and_b32_e32 v20, 0xfffffc00, v20
	v_sub_u32_e32 v2, v2, v20
	v_lshrrev_b32_e32 v20, 4, v2
	v_ashrrev_i32_e32 v21, 31, v210
	v_bitop3_b32 v2, v20, v2, 32 bitop3:0x6c
	v_lshrrev_b32_e32 v21, 26, v21
	v_ashrrev_i32_e32 v20, 31, v2
	v_add_u32_e32 v21, v210, v21
	v_lshrrev_b32_e32 v20, 26, v20
	v_ashrrev_i32_e32 v28, 6, v21
	v_add_u32_e32 v20, v2, v20
	v_lshlrev_b32_e32 v21, 3, v28
	v_ashrrev_i32_e32 v27, 6, v20
	v_and_b32_e32 v21, -16, v21
	v_add_u32_e32 v21, v27, v21
	v_and_b32_e32 v22, 3, v27
	v_lshrrev_b32_e32 v23, 2, v21
	v_lshlrev_b32_e32 v29, 1, v21
	v_and_b32_e32 v20, 0xc0, v20
	v_and_or_b32 v22, v21, s0, v22
	v_and_b32_e32 v23, 4, v23
	v_and_b32_e32 v29, 24, v29
	v_sub_u32_e32 v2, v2, v20
	v_or3_b32 v22, v22, v23, v29
	v_lshlrev_b32_e32 v23, 5, v28
	v_ashrrev_i16_sdwa v2, v30, sext(v2) dst_sel:DWORD dst_unused:UNUSED_PAD src0_sel:DWORD src1_sel:BYTE_0
	v_readlane_b32 s0, v254, 35
	v_and_b32_e32 v23, 32, v23
	v_bfe_i32 v29, v2, 0, 16
	v_readlane_b32 s1, v254, 36
	s_add_u32 s22, s29, s0
	v_add_lshl_u32 v20, v23, v29, 1
	s_addc_u32 s23, s38, s1
	s_add_i32 s39, s28, 0
	v_lshl_add_u32 v2, v22, 12, v20
	s_add_i32 m0, s39, 0x10000
	v_lshl_add_u32 v160, v21, 12, v20
	global_load_lds_dwordx4 v2, s[22:23]
	s_add_i32 m0, s39, 0x12000
	s_add_u32 s0, s22, 0x80000
	global_load_lds_dwordx4 v156, s[22:23]
	s_addc_u32 s1, s23, 0
	s_add_i32 m0, s39, 0x14000
	s_add_i32 s41, s39, 0x2000
	global_load_lds_dwordx4 v2, s[0:1]
	s_add_i32 m0, s39, 0x16000
	s_add_i32 s42, s39, 0x4000
	global_load_lds_dwordx4 v156, s[0:1]
	v_readlane_b32 s0, v254, 41
	s_mov_b32 m0, s39
	v_readlane_b32 s1, v254, 42
	s_add_i32 s43, s39, 0x6000
	s_andn2_b64 vcc, exec, s[4:5]
	s_nop 2
	global_load_lds_dwordx4 v160, s[0:1]
	s_mov_b32 m0, s41
	s_nop 0
	global_load_lds_dwordx4 v158, s[0:1]
	v_readlane_b32 s0, v254, 43
	s_mov_b32 m0, s42
	v_readlane_b32 s1, v254, 44
	s_nop 4
	global_load_lds_dwordx4 v160, s[0:1]
	s_mov_b32 m0, s43
	s_nop 0
	global_load_lds_dwordx4 v158, s[0:1]
	v_readlane_b32 s98, v254, 41
	v_readlane_b32 s99, v254, 42
	s_add_u32 s100, s22, 0x80000
	s_addc_u32 s101, s23, 0
	s_add_i32 m0, s39, 0x17f80
	s_nop 0
	global_load_lds_dwordx4 v2, s[22:23] offset:128
	s_add_i32 m0, s39, 0x19f80
	s_nop 0
	global_load_lds_dwordx4 v156, s[22:23] offset:128
	s_add_i32 m0, s39, 0x7f80
	s_nop 0
	global_load_lds_dwordx4 v160, s[98:99] offset:128
	s_add_i32 m0, s39, 0x9f80
	s_nop 0
	global_load_lds_dwordx4 v158, s[98:99] offset:128
	s_add_i32 m0, s39, 0x1bf80
	s_nop 0
	global_load_lds_dwordx4 v2, s[100:101] offset:128
	s_add_i32 m0, s39, 0x1df80
	s_nop 0
	global_load_lds_dwordx4 v156, s[100:101] offset:128
	s_cbranch_vccnz .LBB0_248
	s_waitcnt vmcnt(14)
	v_add_f32_e32 v20, v16, v17
	v_add_f32_e32 v21, v18, v19
	v_add_f32_e32 v20, v20, v21
	v_add_f32_e32 v21, v12, v13
	v_add_f32_e32 v22, v14, v15
	v_add_f32_e32 v20, 0, v20
	v_add_f32_e32 v21, v21, v22
	v_add_f32_e32 v20, v20, v21
	v_add_f32_e32 v21, v8, v9
	v_add_f32_e32 v22, v10, v11
	v_add_f32_e32 v21, v21, v22
	v_add_f32_e32 v20, v20, v21
	v_add_f32_e32 v21, v4, v5
	v_add_f32_e32 v22, v6, v7
	v_add_f32_e32 v21, v21, v22
	v_and_b32_e32 v22, 64, v208
	v_add_f32_e32 v20, v20, v21
	v_xor_b32_e32 v21, 1, v208
	v_add_u32_e32 v22, 64, v22
	v_cmp_lt_i32_e32 vcc, v21, v22
	v_and_b32_e32 v22, 1, v210
	s_nop 0
	v_cndmask_b32_e32 v21, v208, v21, vcc
	v_lshlrev_b32_e32 v21, 2, v21
	ds_bpermute_b32 v21, v21, v20
	v_cmp_eq_u32_e32 vcc, 0, v22
	s_and_saveexec_b64 s[0:1], vcc
	s_cbranch_execz .LBB0_247
	s_waitcnt lgkmcnt(0)
	v_add_f32_e32 v20, v20, v21
	v_fmamk_f32 v20, v20, 0x3a000000, v1
	v_rsq_f32_e32 v20, v20
	v_lshl_add_u32 v21, v210, 1, 0
	v_add_u32_e32 v21, 0x21000, v21
	ds_write_b32 v21, v20

.LBB0_250:
	s_waitcnt vmcnt(14)
	v_lshrrev_b32_e32 v35, 1, v210
	v_and_b32_e32 v35, 24, v35
	v_and_b32_e32 v34, 15, v210
	v_lshlrev_b32_e32 v36, 1, v35
	v_readlane_b32 s18, v254, 41
	v_lshl_or_b32 v190, s6, 6, v34
	v_lshl_or_b32 v36, v34, 6, v36
	v_lshlrev_b32_e32 v34, 2, v34
	s_lshl_b32 s3, s3, 5
	v_mov_b32_e32 v161, v3
	v_readlane_b32 s19, v254, 42
	s_lshl_b32 s8, s6, 13
	v_and_b32_e32 v37, 32, v34
	s_and_b32 s3, s3, 0x60
	s_add_i32 m0, s39, 0x18000
	v_lshl_add_u64 v[20:21], v[20:21], 0, s[30:31]
	v_lshl_add_u64 v[30:31], s[18:19], 0, v[160:161]
	v_mov_b32_e32 v159, v3
	v_bitop3_b32 v38, v36, s8, v37 bitop3:0xde
	s_lshl_b32 s8, s3, 7
	s_waitcnt vmcnt(8)
	s_barrier
	v_lshl_add_u64 v[20:21], v[22:23], 0, s[30:31]
	s_add_i32 m0, s39, 0x1a000
	s_add_i32 s44, s39, 0x8000
	s_add_i32 s45, s39, 0xa000
	v_lshl_add_u64 v[32:33], s[18:19], 0, v[158:159]
	v_bitop3_b32 v191, s8, v36, v37 bitop3:0xf6
	v_lshl_add_u64 v[20:21], v[30:31], 0, s[30:31]
	s_mov_b32 m0, s44
	s_add_u32 s8, s22, 0x80080
	v_lshl_add_u64 v[20:21], v[32:33], 0, s[30:31]
	s_mov_b32 m0, s45
	s_addc_u32 s9, s23, 0
	s_add_i32 m0, s39, 0x1c000
	v_lshl_add_u64 v[20:21], s[8:9], 0, v[2:3]
	v_lshl_add_u64 v[20:21], s[8:9], 0, v[156:157]
	s_add_i32 m0, s39, 0x1e000
	v_readlane_b32 s8, v252, 45
	v_lshlrev_b32_e32 v20, 2, v35
	v_mov_b32_e32 v21, v3
	v_readlane_b32 s9, v252, 46
	s_cmpk_lt_u32 s2, 0x100
	s_cselect_b64 s[12:13], -1, 0
	v_lshl_add_u64 v[162:163], s[8:9], 0, v[20:21]
	v_lshlrev_b32_e32 v20, 15, v28
	v_and_b32_e32 v20, 0xffff0000, v20
	v_lshl_add_u32 v20, v27, 12, v20
	v_and_b32_e32 v21, 1, v28
	s_lshl_b32 s2, s6, 8
	v_lshl_or_b32 v20, v21, 6, v20
	s_add_i32 s2, s2, 0
	v_lshl_add_u32 v168, v29, 1, v20
	v_lshlrev_b32_e32 v20, 15, v24
	s_add_i32 s2, s2, 0x21000
	v_and_b32_e32 v20, 0xffff0000, v20
	s_waitcnt vmcnt(6)
	v_add_u32_e32 v192, s2, v34
	v_or_b32_e32 v193, s3, v35
	v_lshl_add_u32 v20, v25, 12, v20
	v_and_b32_e32 v21, 1, v24
	v_readlane_b32 s2, v254, 37
	v_lshl_or_b32 v20, v21, 6, v20
	v_readlane_b32 s3, v254, 38
	v_mov_b32_e32 v169, v3
	v_lshl_add_u32 v170, v26, 1, v20
	v_mov_b32_e32 v171, v3
	s_mov_b32 s46, 0
	v_add_u32_e32 v194, 0, v38
	v_readlane_b32 s47, v254, 34
	s_mov_b32 s6, s2
	s_mov_b64 s[2:3], s[18:19]
	s_barrier
	s_branch .LBB0_253

.LBB0_476:
	v_readlane_b32 s0, v255, 9
	v_readlane_b32 s1, v255, 10
	s_mov_b32 s3, s1
	s_lshr_b32 s2, s40, 3
	v_readlane_b32 s0, v252, 3
	v_writelane_b32 v255, s2, 9
	s_cmp_ge_i32 s0, s2
	v_readfirstlane_b32 s6, v210
	v_writelane_b32 v255, s3, 10
	s_cbranch_scc1 .LBB0_500
	v_lshlrev_b32_e32 v2, 4, v210
	s_waitcnt vmcnt(0)
	v_add_u32_e32 v21, 0x2000, v2
	v_ashrrev_i32_e32 v20, 31, v21
	v_lshrrev_b32_e32 v20, 22, v20
	v_add_u32_e32 v20, v21, v20
	v_ashrrev_i32_e32 v20, 10, v20
	v_mul_i32_i24_e32 v22, 0x400, v20
	v_sub_u32_e32 v21, v21, v22
	v_lshrrev_b32_e32 v22, 4, v21
	v_bitop3_b32 v22, v22, v21, 32 bitop3:0x6c
	v_ashrrev_i32_e32 v21, 31, v22
	v_lshrrev_b32_e32 v21, 26, v21
	s_ashr_i32 s8, s6, 6
	v_readlane_b32 s0, v255, 11
	v_add_u32_e32 v23, v22, v21
	v_lshlrev_b32_e32 v24, 3, v20
	s_lshl_b32 s7, s8, 10
	s_lshl_b32 s0, s0, 25
	v_readlane_b32 s1, v253, 14
	v_ashrrev_i32_e32 v21, 6, v23
	v_and_b32_e32 v24, -16, v24
	s_add_u32 s28, s1, s0
	v_readlane_b32 s0, v253, 15
	v_add_u32_e32 v24, v21, v24
	s_addc_u32 s29, s0, 0
	v_and_b32_e32 v25, 3, v21
	s_mov_b32 s0, 0xfffe0
	v_lshrrev_b32_e32 v26, 2, v24
	v_lshlrev_b32_e32 v27, 1, v24
	v_and_b32_e32 v23, 0xc0, v23
	v_and_or_b32 v25, v24, s0, v25
	v_and_b32_e32 v26, 4, v26
	v_and_b32_e32 v27, 24, v27
	v_sub_u32_e32 v22, v22, v23
	v_mov_b32_e32 v30, 1
	v_or3_b32 v25, v25, v26, v27
	v_lshlrev_b32_e32 v26, 5, v20
	v_ashrrev_i16_sdwa v22, v30, sext(v22) dst_sel:DWORD dst_unused:UNUSED_PAD src0_sel:DWORD src1_sel:BYTE_0
	v_and_b32_e32 v26, 32, v26
	v_bfe_i32 v22, v22, 0, 16
	v_add_lshl_u32 v23, v26, v22, 1
	v_lshl_add_u32 v148, v25, 12, v23
	v_lshl_add_u32 v150, v24, 12, v23
	v_bfe_i32 v23, v210, 27, 1
	v_lshrrev_b32_e32 v23, 22, v23
	v_add_u32_e32 v23, v2, v23
	v_and_b32_e32 v23, 0xfffffc00, v23
	v_sub_u32_e32 v2, v2, v23
	v_lshrrev_b32_e32 v23, 4, v2
	v_ashrrev_i32_e32 v24, 31, v210
	v_bitop3_b32 v2, v23, v2, 32 bitop3:0x6c
	v_lshrrev_b32_e32 v24, 26, v24
	v_ashrrev_i32_e32 v23, 31, v2
	v_add_u32_e32 v24, v210, v24
	v_lshrrev_b32_e32 v23, 26, v23
	v_ashrrev_i32_e32 v24, 6, v24
	v_add_u32_e32 v25, v2, v23
	v_lshlrev_b32_e32 v26, 3, v24
	v_ashrrev_i32_e32 v23, 6, v25
	v_and_b32_e32 v26, -16, v26
	v_add_u32_e32 v26, v23, v26
	v_and_b32_e32 v27, 3, v23
	s_lshr_b32 s41, s40, 5
	s_lshr_b32 s40, s40, 6
	v_and_or_b32 v27, v26, s0, v27
	v_readlane_b32 s0, v254, 32
	s_or_b32 s42, s40, 1
	v_readlane_b32 s1, v254, 33
	v_lshrrev_b32_e32 v28, 2, v26
	v_lshlrev_b32_e32 v29, 1, v26
	s_and_b64 s[0:1], s[0:1], exec
	v_and_b32_e32 v28, 4, v28
	v_and_b32_e32 v29, 24, v29
	s_cselect_b32 s0, s42, s40
	s_abs_i32 s43, s41
	v_or3_b32 v27, v27, v28, v29
	v_cvt_f32_u32_e32 v29, s43
	v_and_b32_e32 v25, 0xc0, v25
	v_sub_u32_e32 v2, v2, v25
	v_ashrrev_i16_sdwa v2, v30, sext(v2) dst_sel:DWORD dst_unused:UNUSED_PAD src0_sel:DWORD src1_sel:BYTE_0
	v_bfe_i32 v25, v2, 0, 16
	v_rcp_iflag_f32_e32 v2, v29
	v_readlane_b32 s1, v252, 43
	s_sub_i32 s3, 0, s43
	s_mul_i32 s0, s0, s1
	v_mul_f32_e32 v2, 0x4f7ffffe, v2
	v_cvt_u32_f32_e32 v2, v2
	v_readlane_b32 s1, v252, 44
	s_add_i32 s0, s0, s1
	s_abs_i32 s2, s0
	v_readfirstlane_b32 s45, v2
	s_mul_i32 s3, s3, s45
	s_mul_hi_u32 s3, s45, s3
	s_add_i32 s45, s45, s3
	s_mul_hi_u32 s3, s2, s45
	s_mul_i32 s9, s3, s43
	s_ashr_i32 s1, s0, 31
	s_ashr_i32 s44, s41, 31
	s_sub_i32 s2, s2, s9
	s_xor_b32 s1, s1, s44
	s_add_i32 s9, s3, 1
	s_sub_i32 s12, s2, s43
	s_cmp_ge_u32 s2, s43
	s_cselect_b32 s3, s9, s3
	s_cselect_b32 s2, s12, s2
	s_add_i32 s9, s3, 1
	s_cmp_ge_u32 s2, s43
	s_cselect_b32 s2, s9, s3
	s_xor_b32 s2, s2, s1
	s_sub_i32 s1, s2, s1
	s_lshl_b32 s2, s1, 3
	s_sub_i32 s3, 32, s2
	s_min_i32 s3, s3, 8
	s_abs_i32 s9, s3
	v_cvt_f32_u32_e32 v29, s9
	v_lshlrev_b32_e32 v28, 5, v24
	v_and_b32_e32 v28, 32, v28
	v_add_lshl_u32 v28, v28, v25, 1
	v_lshl_add_u32 v152, v26, 12, v28
	v_rcp_iflag_f32_e32 v26, v29
	s_sub_i32 s13, 0, s9
	s_mul_i32 s1, s1, s41
	s_sub_i32 s0, s0, s1
	v_mul_f32_e32 v26, 0x4f7ffffe, v26
	v_cvt_u32_f32_e32 v26, v26
	s_abs_i32 s12, s0
	s_xor_b32 s1, s0, s3
	s_ashr_i32 s1, s1, 31
	v_readfirstlane_b32 s14, v26
	s_mul_i32 s13, s13, s14
	s_mul_hi_u32 s13, s14, s13
	s_add_i32 s14, s14, s13
	s_mul_hi_u32 s13, s12, s14
	s_mul_i32 s14, s13, s9
	s_sub_i32 s12, s12, s14
	s_add_i32 s14, s13, 1
	s_sub_i32 s15, s12, s9
	s_cmp_ge_u32 s12, s9
	s_cselect_b32 s13, s14, s13
	s_cselect_b32 s12, s15, s12
	s_add_i32 s14, s13, 1
	s_cmp_ge_u32 s12, s9
	s_cselect_b32 s9, s14, s13
	s_xor_b32 s9, s9, s1
	s_sub_i32 s12, s9, s1
	s_mul_i32 s1, s12, s3
	s_sub_i32 s0, s0, s1
	s_add_i32 s2, s0, s2
	s_ashr_i32 s3, s2, 31
	s_ashr_i32 s13, s12, 31
	s_lshl_b64 s[0:1], s[2:3], 20
	s_lshl_b64 s[14:15], s[12:13], 20
	s_add_u32 s26, s28, s14
	s_addc_u32 s27, s29, s15
	s_add_i32 s13, s7, 0
	v_lshl_add_u32 v2, v27, 12, v28
	s_add_i32 m0, s13, 0x10000
	s_nop 0
	global_load_lds_dwordx4 v2, s[26:27]
	s_add_i32 m0, s13, 0x12000
	s_add_u32 s14, s26, 0x80000
	global_load_lds_dwordx4 v148, s[26:27]
	s_addc_u32 s15, s27, 0
	s_add_i32 m0, s13, 0x14000
	s_nop 0
	global_load_lds_dwordx4 v2, s[14:15]
	s_add_i32 m0, s13, 0x16000
	s_nop 0
	global_load_lds_dwordx4 v148, s[14:15]
	v_readlane_b32 s14, v254, 39
	v_readlane_b32 s15, v254, 40
	s_add_u32 s22, s14, s0
	s_addc_u32 s23, s15, s1
	s_add_i32 s46, s13, 0x2000
	s_mov_b32 m0, s13
	s_add_u32 s0, s22, 0x80000
	global_load_lds_dwordx4 v152, s[22:23]
	s_mov_b32 m0, s46
	s_addc_u32 s1, s23, 0
	s_add_i32 s47, s13, 0x4000
	global_load_lds_dwordx4 v150, s[22:23]
	s_mov_b32 m0, s47
	s_add_i32 s48, s13, 0x6000
	global_load_lds_dwordx4 v152, s[0:1]
	s_mov_b32 m0, s48
	s_andn2_b64 vcc, exec, s[4:5]
	global_load_lds_dwordx4 v150, s[0:1]
	s_add_u32 s98, s26, 0x80000
	s_addc_u32 s99, s27, 0
	s_add_i32 m0, s13, 0x17f80
	s_nop 0
	global_load_lds_dwordx4 v2, s[26:27] offset:128
	s_add_i32 m0, s13, 0x19f80
	s_nop 0
	global_load_lds_dwordx4 v148, s[26:27] offset:128
	s_add_i32 m0, s13, 0x7f80
	s_nop 0
	global_load_lds_dwordx4 v152, s[22:23] offset:128
	s_add_i32 m0, s13, 0x9f80
	s_nop 0
	global_load_lds_dwordx4 v150, s[22:23] offset:128
	s_add_i32 m0, s13, 0x1bf80
	s_nop 0
	global_load_lds_dwordx4 v2, s[98:99] offset:128
	s_add_i32 m0, s13, 0x1df80
	s_nop 0
	global_load_lds_dwordx4 v148, s[98:99] offset:128
	s_cbranch_vccnz .LBB0_481
	v_add_f32_e32 v16, v16, v17
	v_add_f32_e32 v17, v18, v19
	v_add_f32_e32 v16, v16, v17
	v_add_f32_e32 v12, v12, v13
	v_add_f32_e32 v13, v14, v15
	v_add_f32_e32 v4, v4, v5
	v_add_f32_e32 v5, v6, v7
	v_and_b32_e32 v6, 64, v208
	v_add_f32_e32 v16, 0, v16
	v_add_f32_e32 v12, v12, v13
	v_add_f32_e32 v8, v8, v9
	v_add_f32_e32 v9, v10, v11
	v_add_f32_e32 v4, v4, v5
	v_xor_b32_e32 v5, 1, v208
	v_add_u32_e32 v6, 64, v6
	v_add_f32_e32 v12, v16, v12
	v_add_f32_e32 v8, v8, v9
	v_cmp_lt_i32_e32 vcc, v5, v6
	v_add_f32_e32 v8, v12, v8
	v_add_f32_e32 v4, v8, v4
	v_cndmask_b32_e32 v5, v208, v5, vcc
	v_lshlrev_b32_e32 v5, 2, v5
	ds_bpermute_b32 v5, v5, v4
	v_and_b32_e32 v6, 1, v210
	v_cmp_eq_u32_e32 vcc, 0, v6
	s_and_saveexec_b64 s[0:1], vcc
	s_cbranch_execz .LBB0_480
	s_waitcnt lgkmcnt(0)
	v_add_f32_e32 v4, v4, v5
	v_fmamk_f32 v4, v4, 0x3a000000, v1
	v_rsq_f32_e32 v4, v4
	v_lshl_add_u32 v5, v210, 1, 0
	v_add_u32_e32 v5, 0x21000, v5
	ds_write_b32 v5, v4

.LBB0_483:
	v_bfe_u32 v13, v210, 4, 2
	v_and_b32_e32 v12, 15, v210
	v_lshlrev_b32_e32 v163, 4, v13
	v_lshl_or_b32 v162, s3, 6, v12
	v_lshl_or_b32 v14, v12, 6, v163
	v_lshlrev_b32_e32 v12, 2, v12
	s_and_b32 s8, s8, 3
	s_lshl_b32 s4, s3, 13
	v_and_b32_e32 v15, 32, v12
	s_add_i32 m0, s13, 0x18000
	v_lshl_add_u64 v[6:7], v[6:7], 0, s[30:31]
	v_bitop3_b32 v16, v14, s4, v15 bitop3:0xde
	s_lshl_b32 s4, s8, 12
	s_waitcnt vmcnt(8)
	s_barrier
	v_lshl_add_u64 v[6:7], v[8:9], 0, s[30:31]
	s_add_i32 m0, s13, 0x1a000
	s_add_i32 s49, s13, 0x8000
	s_add_i32 s50, s13, 0xa000
	v_bitop3_b32 v168, s4, v14, v15 bitop3:0xf6
	v_lshl_add_u64 v[4:5], v[4:5], 0, s[30:31]
	s_mov_b32 m0, s49
	s_add_u32 s4, s26, 0x80080
	v_lshl_add_u64 v[4:5], v[10:11], 0, s[30:31]
	s_mov_b32 m0, s50
	s_addc_u32 s5, s27, 0
	s_add_i32 m0, s13, 0x1c000
	v_lshl_add_u64 v[4:5], s[4:5], 0, v[2:3]
	v_lshl_add_u64 v[4:5], s[4:5], 0, v[148:149]
	s_add_i32 m0, s13, 0x1e000
	s_cmpk_lt_u32 s6, 0x100
	s_cselect_b64 s[4:5], -1, 0
	s_lshl_b32 s51, s8, 6
	v_readlane_b32 s8, v252, 45
	v_lshlrev_b32_e32 v4, 5, v13
	v_mov_b32_e32 v5, v3
	v_readlane_b32 s9, v252, 46
	s_lshl_b32 s3, s3, 8
	s_waitcnt vmcnt(6)
	s_add_i32 s3, s3, 0
	v_lshl_add_u64 v[154:155], s[8:9], 0, v[4:5]
	v_lshlrev_b32_e32 v4, 15, v24
	v_and_b32_e32 v4, 0xffff0000, v4
	v_lshl_add_u32 v4, v23, 12, v4
	v_and_b32_e32 v5, 1, v24
	v_lshl_or_b32 v4, v5, 6, v4
	v_lshl_add_u32 v156, v25, 1, v4
	v_lshlrev_b32_e32 v4, 15, v20
	v_and_b32_e32 v4, 0xffff0000, v4
	v_lshl_add_u32 v4, v21, 12, v4
	v_and_b32_e32 v5, 1, v20
	s_add_i32 s3, s3, 0x21000
	v_lshl_or_b32 v4, v5, 6, v4
	v_add_u32_e32 v169, s3, v12
	v_mov_b32_e32 v157, v3
	v_lshl_add_u32 v158, v22, 1, v4
	v_mov_b32_e32 v159, v3
	s_mov_b32 s52, 0
	v_add_u32_e32 v170, 0, v16
	s_barrier
	s_branch .LBB0_486

.LBB0_815:
	v_readlane_b32 s0, v254, 29
	v_readlane_b32 s1, v254, 30
	s_andn2_b64 vcc, exec, s[0:1]
	v_readfirstlane_b32 s6, v210
	s_cbranch_vccnz .LBB0_841
	v_lshlrev_b32_e32 v2, 4, v210
	s_waitcnt vmcnt(0)
	v_add_u32_e32 v4, 0x2000, v2
	v_ashrrev_i32_e32 v5, 31, v4
	v_lshrrev_b32_e32 v5, 22, v5
	v_add_u32_e32 v5, v4, v5
	v_ashrrev_i32_e32 v5, 10, v5
	v_mul_i32_i24_e32 v6, 0x400, v5
	v_sub_u32_e32 v4, v4, v6
	v_lshrrev_b32_e32 v6, 4, v4
	v_bitop3_b32 v6, v6, v4, 32 bitop3:0x6c
	s_ashr_i32 s9, s6, 6
	v_readlane_b32 s0, v255, 15
	v_ashrrev_i32_e32 v4, 31, v6
	s_lshl_b32 s16, s7, 8
	s_lshl_b32 s25, s7, 9
	s_ashr_i32 s8, s6, 8
	s_lshl_b32 s26, s9, 10
	v_readlane_b32 s1, v255, 16
	v_lshrrev_b32_e32 v4, 26, v4
	s_and_b64 s[0:1], s[0:1], exec
	v_readlane_b32 s2, v252, 55
	v_add_u32_e32 v7, v6, v4
	v_lshlrev_b32_e32 v8, 3, v5
	v_readlane_b32 s0, v252, 54
	v_readlane_b32 s3, v252, 56
	v_ashrrev_i32_e32 v4, 6, v7
	v_and_b32_e32 v8, -16, v8
	s_cselect_b32 s27, s0, s3
	v_readlane_b32 s0, v252, 53
	v_add_u32_e32 v8, v4, v8
	s_cselect_b32 s46, s0, s2
	v_and_b32_e32 v4, 3, v4
	s_mov_b32 s0, 0x7fffffe0
	v_lshrrev_b32_e32 v9, 2, v8
	v_lshlrev_b32_e32 v10, 1, v8
	v_and_or_b32 v4, v8, s0, v4
	v_and_b32_e32 v9, 4, v9
	v_and_b32_e32 v10, 24, v10
	v_or3_b32 v4, v4, v9, v10
	v_mul_lo_u32 v9, v4, s7
	v_lshlrev_b32_e32 v4, 5, v5
	v_and_b32_e32 v5, 0xc0, v7
	v_sub_u32_e32 v5, v6, v5
	v_mov_b32_e32 v13, 1
	v_ashrrev_i16_sdwa v5, v13, sext(v5) dst_sel:DWORD dst_unused:UNUSED_PAD src0_sel:DWORD src1_sel:BYTE_0
	v_and_b32_e32 v4, 32, v4
	v_bfe_i32 v5, v5, 0, 16
	v_add_u32_e32 v7, v4, v5
	v_mul_lo_u32 v6, v8, s7
	v_add_lshl_u32 v132, v9, v7, 1
	v_add_lshl_u32 v134, v7, v6, 1
	v_bfe_i32 v7, v210, 27, 1
	v_lshrrev_b32_e32 v7, 22, v7
	v_add_u32_e32 v7, v2, v7
	v_and_b32_e32 v7, 0xfffffc00, v7
	v_sub_u32_e32 v2, v2, v7
	v_lshrrev_b32_e32 v7, 4, v2
	v_ashrrev_i32_e32 v9, 31, v210
	v_bitop3_b32 v7, v7, v2, 32 bitop3:0x6c
	v_lshrrev_b32_e32 v9, 26, v9
	v_ashrrev_i32_e32 v2, 31, v7
	v_add_u32_e32 v9, v210, v9
	v_lshrrev_b32_e32 v2, 26, v2
	v_ashrrev_i32_e32 v9, 6, v9
	v_add_u32_e32 v8, v7, v2
	v_lshlrev_b32_e32 v10, 3, v9
	v_ashrrev_i32_e32 v2, 6, v8
	v_and_b32_e32 v10, -16, v10
	v_add_u32_e32 v10, v2, v10
	v_and_b32_e32 v2, 3, v2
	v_and_or_b32 v2, v10, s0, v2
	v_lshrrev_b32_e32 v11, 2, v10
	v_lshlrev_b32_e32 v12, 1, v10
	v_readlane_b32 s0, v254, 53
	v_and_b32_e32 v11, 4, v11
	v_and_b32_e32 v12, 24, v12
	v_and_b32_e32 v8, 0xc0, v8
	s_mul_hi_i32 s3, s25, s0
	s_mul_i32 s2, s25, s0
	v_readlane_b32 s0, v254, 55
	v_or3_b32 v2, v2, v11, v12
	v_sub_u32_e32 v7, v7, v8
	v_readlane_b32 s1, v254, 56
	s_mov_b32 s12, s0
	v_mul_lo_u32 v11, v2, s7
	v_lshlrev_b32_e32 v2, 5, v9
	v_ashrrev_i16_sdwa v7, v13, sext(v7) dst_sel:DWORD dst_unused:UNUSED_PAD src0_sel:DWORD src1_sel:BYTE_0
	s_mul_i32 s1, s25, s12
	v_and_b32_e32 v2, 32, v2
	v_bfe_i32 v7, v7, 0, 16
	s_mul_hi_i32 s0, s25, s0
	s_add_u32 s22, s4, s1
	v_add_u32_e32 v9, v2, v7
	s_addc_u32 s23, s5, s0
	s_add_i32 s47, s26, 0
	v_add_lshl_u32 v136, v11, v9, 1
	s_add_i32 m0, s47, 0x10000
	v_mul_lo_u32 v8, v10, s7
	global_load_lds_dwordx4 v136, s[22:23]
	s_add_i32 m0, s47, 0x12000
	s_add_u32 s0, s22, s16
	global_load_lds_dwordx4 v132, s[22:23]
	s_addc_u32 s1, s23, 0
	s_add_i32 m0, s47, 0x14000
	v_add_lshl_u32 v138, v9, v8, 1
	global_load_lds_dwordx4 v136, s[0:1]
	s_add_i32 m0, s47, 0x16000
	s_add_u32 s2, s46, s2
	s_addc_u32 s3, s27, s3
	s_add_i32 s48, s47, 0x2000
	global_load_lds_dwordx4 v132, s[0:1]
	s_mov_b32 m0, s47
	s_add_u32 s12, s2, s16
	global_load_lds_dwordx4 v138, s[2:3]
	s_mov_b32 m0, s48
	s_addc_u32 s13, s3, 0
	s_add_i32 s49, s47, 0x4000
	global_load_lds_dwordx4 v134, s[2:3]
	s_mov_b32 m0, s49
	s_add_i32 s50, s47, 0x6000
	global_load_lds_dwordx4 v138, s[12:13]
	s_mov_b32 m0, s50
	v_readlane_b32 s18, v255, 9
	global_load_lds_dwordx4 v134, s[12:13]
	s_add_i32 m0, s47, 0x17f80
	s_nop 0
	global_load_lds_dwordx4 v136, s[22:23] offset:128
	s_add_i32 m0, s47, 0x19f80
	s_nop 0
	global_load_lds_dwordx4 v132, s[22:23] offset:128
	s_add_i32 m0, s47, 0x7f80
	s_nop 0
	global_load_lds_dwordx4 v138, s[2:3] offset:128
	s_add_i32 m0, s47, 0x9f80
	s_nop 0
	global_load_lds_dwordx4 v134, s[2:3] offset:128
	s_add_i32 m0, s47, 0x1bf80
	s_nop 0
	global_load_lds_dwordx4 v136, s[0:1] offset:128
	s_add_i32 m0, s47, 0x1df80
	s_nop 0
	global_load_lds_dwordx4 v132, s[0:1] offset:128
	s_cmp_eq_u32 s8, 1
	v_readlane_b32 s19, v255, 10
	s_cselect_b64 s[12:13], -1, 0
	s_cmp_lg_u32 s8, 1
	s_mov_b32 s17, s19
	s_cbranch_scc1 .LBB0_818
	s_barrier
.LBB0_818:
	v_mov_b32_e32 v137, v3
	v_lshl_add_u64 v[10:11], s[22:23], 0, v[136:137]
	v_mov_b32_e32 v133, v3
	v_lshl_add_u64 v[12:13], s[22:23], 0, v[132:133]
	v_mov_b32_e32 v139, v3
	s_add_i32 m0, s47, 0x18000
	v_lshl_add_u64 v[10:11], v[10:11], 0, s[30:31]
	s_waitcnt lgkmcnt(0)
	v_lshl_add_u64 v[18:19], s[2:3], 0, v[138:139]
	v_mov_b32_e32 v135, v3
	s_waitcnt vmcnt(8)
	s_barrier
	v_lshl_add_u64 v[10:11], v[12:13], 0, s[30:31]
	s_add_i32 m0, s47, 0x1a000
	s_add_i32 s53, s47, 0x8000
	v_lshl_add_u64 v[20:21], s[2:3], 0, v[134:135]
	v_lshl_add_u64 v[10:11], v[18:19], 0, s[30:31]
	s_mov_b32 m0, s53
	s_add_i32 s54, s47, 0xa000
	v_lshl_add_u64 v[14:15], s[0:1], 0, v[136:137]
	v_lshl_add_u64 v[10:11], v[20:21], 0, s[30:31]
	s_mov_b32 m0, s54
	v_lshl_add_u64 v[16:17], s[0:1], 0, v[132:133]
	s_add_i32 m0, s47, 0x1c000
	v_lshl_add_u64 v[10:11], v[14:15], 0, s[30:31]
	v_lshl_add_u64 v[10:11], v[16:17], 0, s[30:31]
	s_add_i32 m0, s47, 0x1e000
	v_bfe_u32 v22, v210, 4, 2
	v_and_b32_e32 v23, 15, v210
	v_lshlrev_b32_e32 v24, 4, v22
	v_lshlrev_b32_e32 v25, 2, v210
	s_lshr_b32 s51, s7, 6
	s_and_b32 s0, s9, 3
	v_lshl_or_b32 v146, s8, 6, v23
	v_lshl_or_b32 v23, v23, 6, v24
	s_lshl_b32 s1, s8, 13
	v_and_b32_e32 v25, 32, v25
	s_add_i32 s52, s51, -2
	v_bitop3_b32 v26, v23, s1, v25 bitop3:0xde
	s_lshl_b32 s1, s0, 12
	v_add_u32_e32 v2, v8, v2
	s_cmpk_lt_u32 s6, 0x100
	v_add_lshl_u32 v2, v2, v7, 1
	v_readlane_b32 s6, v255, 9
	v_lshrrev_b32_e32 v9, 4, v210
	s_waitcnt vmcnt(6)
	s_cselect_b64 s[18:19], -1, 0
	v_lshl_add_u64 v[140:141], s[16:17], 0, v[2:3]
	v_add_u32_e32 v2, v6, v4
	v_readlane_b32 s7, v255, 10
	s_lshl_b32 s6, s0, 2
	v_bitop3_b32 v147, s1, v23, v25 bitop3:0xf6
	v_lshlrev_b32_e32 v9, 6, v9
	v_lshlrev_b32_e32 v10, 5, v22
	s_movk_i32 s1, 0xa0
	v_add_lshl_u32 v2, v2, v5, 1
	v_writelane_b32 v255, s6, 9
	s_mov_b32 s55, 0
	v_cmp_eq_u32_e64 s[36:37], 0, v22
	v_cmp_ne_u32_e64 s[38:39], 0, v22
	v_cmp_eq_u32_e64 s[40:41], 1, v22
	v_cmp_eq_u32_e64 s[42:43], 2, v22
	v_bitop3_b32 v148, v9, s1, v10 bitop3:0xc8
	s_mov_b32 s15, s14
	v_lshl_or_b32 v149, s0, 6, v24
	v_lshl_add_u64 v[142:143], s[16:17], 0, v[2:3]
	v_add_u32_e32 v150, 0, v26
	v_writelane_b32 v255, s7, 10
	v_readlane_b32 s17, v254, 54
	v_readlane_b32 s6, v254, 53
	s_barrier
	s_branch .LBB0_821
